# GLA: nt cache policy on the once-read gv LDS-DMA stream
# speedup vs baseline: 1.0070x; 1.0070x over previous
; __device__ __forceinline__ void gla_item(LAS unsigned char* lds, int item, const bf16_t* KDT, const float* DEC, const bf16_t* GVT, const bf16_t* GQF, bf16_t* OG) {
;     const int tid = threadIdx.x, wid = __builtin_amdgcn_readfirstlane(tid >> 6), lane = tid & 63, fr = lane & 15, fq = lane >> 4;
;     const int vs = item & 7, h = (item >> 3) & 3, b = item >> 5;
;     const bf16_t* kdt = KDT + (size_t)((b * 4 + h) * 32) * 8192 + (size_t)(wid * 2 * 64 + lane) * 8;
;     const float* dec = DEC + (size_t)((b * 4 + h) * 32) * 128 + 16 * wid + 4 * fq;
;     const bf16_t* gvt = GVT + (size_t)item * (32 * 4 * 512) + (size_t)lane * 8;
;     const int f0 = 16 * (wid & 3), v0 = 16 * (wid >> 2);
;     const bf16_t* gq = GQF + ((size_t)((b * 4 + h) * 32) * 16 + (size_t)(wid & 3) * 4) * 512 + (size_t)lane * 8;
;     bf16_t* outp = OG + (size_t)item * (SEQ * 32) + (size_t)(f0 + fr) * 32 + v0 + 4 * fq;
;     f32x4 S[2]; S[0] = (f32x4){0.f, 0.f, 0.f, 0.f}; S[1] = S[0];
;     ...
;     GlaSet s0, s1, s2;
;     GLA_LOAD(s0, 0); GLA_LOAD(s1, 1);
; #pragma unroll 1
;     for (int c = 0; c < 30; c += 3) {
;         GLA_LOAD(s2, c + 2); GLA_STEP(s0, c);
;         GLA_LOAD(s0, c + 3); GLA_STEP(s1, c + 1);
;         GLA_LOAD(s1, c + 4); GLA_STEP(s2, c + 2);
;     }
.LBB0_982:
	v_readfirstlane_b32 s53, v185
	v_lshlrev_b32_e32 v0, 4, v184
	v_lshrrev_b32_e32 v6, 4, v184
	v_and_b32_e32 v7, 15, v184
	s_lshr_b32 s53, s53, 6
	v_lshlrev_b32_e32 v1, 4, v6
	s_and_b32 s0, s52, 7
	s_lshl_b32 s0, s0, 2
	s_lshr_b32 s55, s52, 6
	s_add_i32 s0, s0, s55
	s_bfe_u32 s55, s52, 0x30003
	s_lshl_b32 s69, s0, 3
	s_add_i32 s69, s69, s55
	s_lshl_b32 s36, s0, 19
	s_lshl_b32 s37, s53, 11
	s_add_i32 s36, s36, s37
	s_add_u32 s58, s86, 0x14000000
	s_addc_u32 s59, s87, 0
	s_add_u32 s58, s58, s36
	s_addc_u32 s59, s59, 0
	s_lshl_b32 s36, s0, 14
	s_lshl_b32 s37, s53, 6
	s_add_i32 s36, s36, s37
	s_add_u32 s60, s86, 0x15000000
	s_addc_u32 s61, s87, 0
	s_add_u32 s60, s60, s36
	s_addc_u32 s61, s61, 0
	s_lshl_b32 s36, s69, 17
	s_add_u32 s62, s86, 0x10800000
	s_addc_u32 s63, s87, 0
	s_add_u32 s62, s62, s36
	s_addc_u32 s63, s63, 0
	s_add_u32 s66, s86, 0x1e000000
	s_addc_u32 s67, s87, 0
	s_add_u32 s66, s66, s36
	s_addc_u32 s67, s67, 0
	s_and_b32 s36, s53, 3
	s_lshl_b32 s36, s36, 12
	s_lshr_b32 s37, s53, 2
	s_lshl_b32 s37, s37, 11
	s_add_i32 s55, s36, s37
	s_lshl_b32 s37, s0, 19
	s_add_u32 s64, s86, 0x6800000
	s_addc_u32 s65, s87, 0
	s_add_u32 s64, s64, s37
	s_addc_u32 s65, s65, 0
	s_add_u32 s64, s64, s55
	s_addc_u32 s65, s65, 0
	s_add_i32 s36, s36, 0x1000
	v_add_u32_e32 v108, s36, v0
	s_and_b32 s36, s53, 3
	s_lshl_b32 s36, s36, 4
	v_add_u32_e32 v2, s36, v7
	v_lshlrev_b32_e32 v2, 5, v2
	s_lshr_b32 s37, s53, 2
	s_lshl_b32 s37, s37, 4
	v_lshl_add_u32 v2, v6, 2, v2
	v_add_u32_e32 v2, s37, v2
	v_lshlrev_b32_e32 v2, 1, v2
	v_mul_u32_u24_e32 v3, 0x110, v7
	s_lshl_b32 s36, s53, 5
	v_lshl_add_u32 v3, v6, 3, v3
	v_add_u32_e32 v3, s36, v3
	v_add_u32_e32 v4, s37, v7
	v_mul_u32_u24_e32 v4, 0x110, v4
	v_lshl_add_u32 v4, v6, 4, v4
	s_lshr_b32 s36, s53, 1
	s_lshl_b32 s36, s36, 10
	v_add_u32_e32 v109, s36, v0
	s_and_b32 s37, s53, 1
	s_add_i32 s53, s55, 0x1000
	s_mov_b32 s55, s36
	s_cmp_lg_u32 s37, 0
	s_cselect_b32 s36, 0, -1
	s_cselect_b32 s37, -1, 0
	s_mov_b32 s0, 0x5000
	s_mov_b64 exec, s[36:37]
	s_add_i32 m0, s0, s55
	s_nop 0
	global_load_lds_dwordx4 v109, s[62:63] nt
	s_mov_b64 exec, -1
	s_add_i32 m0, s0, s53
	s_nop 0
	global_load_lds_dwordx4 v0, s[64:65]
	global_load_lds_dwordx4 v0, s[64:65] offset:1024
	s_add_u32 s62, s62, 0x1000
	s_addc_u32 s63, s63, 0
	s_add_u32 s64, s64, 0x4000
	s_addc_u32 s65, s65, 0
	s_mov_b32 s0, 0xa000
	s_mov_b64 exec, s[36:37]
	s_add_i32 m0, s0, s55
	s_nop 0
	global_load_lds_dwordx4 v109, s[62:63] nt
	s_mov_b64 exec, -1
	s_add_i32 m0, s0, s53
	s_nop 0
	global_load_lds_dwordx4 v0, s[64:65]
	global_load_lds_dwordx4 v0, s[64:65] offset:1024
	s_add_u32 s62, s62, 0x1000
	s_addc_u32 s63, s63, 0
	s_add_u32 s64, s64, 0x4000
	s_addc_u32 s65, s65, 0
	s_mov_b32 s0, 0xf000
	s_mov_b64 exec, s[36:37]
	s_add_i32 m0, s0, s55
	s_nop 0
	global_load_lds_dwordx4 v109, s[62:63] nt
	s_mov_b64 exec, -1
	s_add_i32 m0, s0, s53
	s_nop 0
	global_load_lds_dwordx4 v0, s[64:65]
	global_load_lds_dwordx4 v0, s[64:65] offset:1024
	s_add_u32 s62, s62, 0x1000
	s_addc_u32 s63, s63, 0
	s_add_u32 s64, s64, 0x4000
	s_addc_u32 s65, s65, 0
	global_load_dwordx4 v[16:19], v0, s[58:59]
	global_load_dwordx4 v[20:23], v0, s[58:59] offset:1024
	global_load_dwordx4 v[24:27], v1, s[60:61]
	s_add_u32 s58, s58, 0x4000
	s_addc_u32 s59, s59, 0
	s_add_u32 s60, s60, 0x200
	s_addc_u32 s61, s61, 0
	global_load_dwordx4 v[28:31], v0, s[58:59]
	global_load_dwordx4 v[32:35], v0, s[58:59] offset:1024
	global_load_dwordx4 v[36:39], v1, s[60:61]
	s_add_u32 s58, s58, 0x4000
	s_addc_u32 s59, s59, 0
	s_add_u32 s60, s60, 0x200
	s_addc_u32 s61, s61, 0
	v_mov_b32_e32 v8, 0
	v_mov_b32_e32 v9, 0
	v_mov_b32_e32 v10, 0
	v_mov_b32_e32 v11, 0
	v_mov_b32_e32 v12, 0
	v_mov_b32_e32 v13, 0
	v_mov_b32_e32 v14, 0
	v_mov_b32_e32 v15, 0
	s_mov_b32 s54, 0
	s_mov_b32 s68, 0x5000
	s_waitcnt vmcnt(0)
	s_barrier
.Lgla_loop:
	s_waitcnt vmcnt(11)
	v_add_u32_e32 v5, s68, v0
	ds_read_b128 v[52:55], v5
	ds_read_b128 v[56:59], v5 offset:1024
	ds_read_b128 v[60:63], v5 offset:2048
	ds_read_b128 v[64:67], v5 offset:3072
	v_pk_mul_f32 v[8:9], v[8:9], v[24:25]
	v_pk_mul_f32 v[10:11], v[10:11], v[26:27]
	v_pk_mul_f32 v[12:13], v[12:13], v[24:25]
	v_pk_mul_f32 v[14:15], v[14:15], v[26:27]
	s_and_b32 s69, s54, 1
	s_mulk_i32 s69, 0x2200
	v_add_u32_e32 v6, s69, v3
	v_add_u32_e32 v7, s69, v4
	s_waitcnt lgkmcnt(0)
	s_nop 0
	v_mfma_f32_16x16x32_bf16 v[8:11], v[16:19], v[52:55], v[8:11]
	v_mfma_f32_16x16x32_bf16 v[12:15], v[16:19], v[60:63], v[12:15]
	v_mfma_f32_16x16x32_bf16 v[8:11], v[20:23], v[56:59], v[8:11]
	v_mfma_f32_16x16x32_bf16 v[12:15], v[20:23], v[64:67], v[12:15]
	global_load_dwordx4 v[40:43], v0, s[58:59]
	global_load_dwordx4 v[44:47], v0, s[58:59] offset:1024
	global_load_dwordx4 v[48:51], v1, s[60:61]
	s_add_u32 s58, s58, 0x4000
	s_addc_u32 s59, s59, 0
	s_add_u32 s60, s60, 0x200
	s_addc_u32 s61, s61, 0
	s_nop 7
	v_cvt_pk_bf16_f32 v104, v8, v9
	v_cvt_pk_bf16_f32 v105, v10, v11
	v_cvt_pk_bf16_f32 v106, v12, v13
	v_cvt_pk_bf16_f32 v107, v14, v15
	ds_write_b64 v6, v[104:105]
	ds_write_b64 v6, v[106:107] offset:4352
	s_waitcnt vmcnt(11)
	s_waitcnt lgkmcnt(0)
	s_barrier
	v_add_u32_e32 v5, s68, v108
	ds_read_b128 v[68:71], v7
	ds_read_b128 v[72:75], v7 offset:64
	ds_read_b128 v[76:79], v7 offset:128
	ds_read_b128 v[80:83], v7 offset:192
	ds_read_b128 v[84:87], v5
	ds_read_b128 v[88:91], v5 offset:1024
	ds_read_b128 v[92:95], v5 offset:2048
	ds_read_b128 v[96:99], v5 offset:3072
	s_add_i32 s0, s68, 0xffffb000
	s_cmp_lg_u32 s68, 0x5000
	s_cselect_b32 s0, s0, 0x14000
	s_mov_b64 exec, s[36:37]
	s_add_i32 m0, s0, s55
	s_nop 0
	global_load_lds_dwordx4 v109, s[62:63] nt
	s_mov_b64 exec, -1
	s_add_i32 m0, s0, s53
	s_nop 0
	global_load_lds_dwordx4 v0, s[64:65]
	global_load_lds_dwordx4 v0, s[64:65] offset:1024
	s_add_u32 s62, s62, 0x1000
	s_addc_u32 s63, s63, 0
	s_add_u32 s64, s64, 0x4000
	s_addc_u32 s65, s65, 0
	s_waitcnt lgkmcnt(0)
	v_mfma_f32_16x16x32_bf16 v[100:103], v[68:71], v[84:87], 0
	v_mfma_f32_16x16x32_bf16 v[100:103], v[72:75], v[88:91], v[100:103]
	v_mfma_f32_16x16x32_bf16 v[100:103], v[76:79], v[92:95], v[100:103]
	v_mfma_f32_16x16x32_bf16 v[100:103], v[80:83], v[96:99], v[100:103]
	s_add_i32 s68, s68, 0x5000
	s_cmp_lg_u32 s68, 0x19000
	s_cselect_b32 s68, s68, 0x5000
	s_nop 7
	v_pk_mul_f32 v[100:101], v[100:101], s[22:23] op_sel_hi:[1,0]
	v_pk_mul_f32 v[102:103], v[102:103], s[22:23] op_sel_hi:[1,0]
	s_cmpk_lt_u32 s54, 0x20
	v_cvt_pk_bf16_f32 v104, v100, v101
	v_cvt_pk_bf16_f32 v105, v102, v103
	s_cbranch_scc0 .Lgla_nost0
	global_store_dwordx2 v2, v[104:105], s[66:67]
; __device__ __forceinline__ void gla_item(LAS unsigned char* lds, int item, const bf16_t* KDT, const float* DEC, const bf16_t* GVT, const bf16_t* GQF, bf16_t* OG) {
;     ...
;     for (int c = 0; c < 30; c += 3) {
;         GLA_LOAD(s2, c + 2); GLA_STEP(s0, c);
;         GLA_LOAD(s0, c + 3); GLA_STEP(s1, c + 1);
;         GLA_LOAD(s1, c + 4); GLA_STEP(s2, c + 2);
;     }
.Lgla_nost0:
	s_add_u32 s66, s66, 0x1000
	s_addc_u32 s67, s67, 0
	s_add_i32 s54, s54, 1
	s_waitcnt vmcnt(11)
	v_add_u32_e32 v5, s68, v0
	ds_read_b128 v[52:55], v5
	ds_read_b128 v[56:59], v5 offset:1024
	ds_read_b128 v[60:63], v5 offset:2048
	ds_read_b128 v[64:67], v5 offset:3072
	v_pk_mul_f32 v[8:9], v[8:9], v[36:37]
	v_pk_mul_f32 v[10:11], v[10:11], v[38:39]
	v_pk_mul_f32 v[12:13], v[12:13], v[36:37]
	v_pk_mul_f32 v[14:15], v[14:15], v[38:39]
	s_and_b32 s69, s54, 1
	s_mulk_i32 s69, 0x2200
	v_add_u32_e32 v6, s69, v3
	v_add_u32_e32 v7, s69, v4
	s_waitcnt lgkmcnt(0)
	s_nop 0
	v_mfma_f32_16x16x32_bf16 v[8:11], v[28:31], v[52:55], v[8:11]
	v_mfma_f32_16x16x32_bf16 v[12:15], v[28:31], v[60:63], v[12:15]
	v_mfma_f32_16x16x32_bf16 v[8:11], v[32:35], v[56:59], v[8:11]
	v_mfma_f32_16x16x32_bf16 v[12:15], v[32:35], v[64:67], v[12:15]
	global_load_dwordx4 v[16:19], v0, s[58:59]
	global_load_dwordx4 v[20:23], v0, s[58:59] offset:1024
	global_load_dwordx4 v[24:27], v1, s[60:61]
	s_add_u32 s58, s58, 0x4000
	s_addc_u32 s59, s59, 0
	s_add_u32 s60, s60, 0x200
	s_addc_u32 s61, s61, 0
	s_nop 7
	v_cvt_pk_bf16_f32 v104, v8, v9
	v_cvt_pk_bf16_f32 v105, v10, v11
	v_cvt_pk_bf16_f32 v106, v12, v13
	v_cvt_pk_bf16_f32 v107, v14, v15
	ds_write_b64 v6, v[104:105]
	ds_write_b64 v6, v[106:107] offset:4352
	s_waitcnt vmcnt(11)
	s_waitcnt lgkmcnt(0)
	s_barrier
	v_add_u32_e32 v5, s68, v108
	ds_read_b128 v[68:71], v7
	ds_read_b128 v[72:75], v7 offset:64
	ds_read_b128 v[76:79], v7 offset:128
	ds_read_b128 v[80:83], v7 offset:192
	ds_read_b128 v[84:87], v5
	ds_read_b128 v[88:91], v5 offset:1024
	ds_read_b128 v[92:95], v5 offset:2048
	ds_read_b128 v[96:99], v5 offset:3072
	s_add_i32 s0, s68, 0xffffb000
	s_cmp_lg_u32 s68, 0x5000
	s_cselect_b32 s0, s0, 0x14000
	s_mov_b64 exec, s[36:37]
	s_add_i32 m0, s0, s55
	s_nop 0
	global_load_lds_dwordx4 v109, s[62:63] nt
	s_mov_b64 exec, -1
	s_add_i32 m0, s0, s53
	s_nop 0
	global_load_lds_dwordx4 v0, s[64:65]
	global_load_lds_dwordx4 v0, s[64:65] offset:1024
	s_add_u32 s62, s62, 0x1000
	s_addc_u32 s63, s63, 0
	s_add_u32 s64, s64, 0x4000
	s_addc_u32 s65, s65, 0
	s_waitcnt lgkmcnt(0)
	v_mfma_f32_16x16x32_bf16 v[100:103], v[68:71], v[84:87], 0
	v_mfma_f32_16x16x32_bf16 v[100:103], v[72:75], v[88:91], v[100:103]
	v_mfma_f32_16x16x32_bf16 v[100:103], v[76:79], v[92:95], v[100:103]
	v_mfma_f32_16x16x32_bf16 v[100:103], v[80:83], v[96:99], v[100:103]
	s_add_i32 s68, s68, 0x5000
	s_cmp_lg_u32 s68, 0x19000
	s_cselect_b32 s68, s68, 0x5000
	s_nop 7
	v_pk_mul_f32 v[100:101], v[100:101], s[22:23] op_sel_hi:[1,0]
	v_pk_mul_f32 v[102:103], v[102:103], s[22:23] op_sel_hi:[1,0]
	s_cmpk_lt_u32 s54, 0x20
	v_cvt_pk_bf16_f32 v104, v100, v101
	v_cvt_pk_bf16_f32 v105, v102, v103
	s_cbranch_scc0 .Lgla_nost1
	global_store_dwordx2 v2, v[104:105], s[66:67]
.Lgla_nost1:
	s_add_u32 s66, s66, 0x1000
	s_addc_u32 s67, s67, 0
	s_add_i32 s54, s54, 1
	s_waitcnt vmcnt(11)
	v_add_u32_e32 v5, s68, v0
	ds_read_b128 v[52:55], v5
	ds_read_b128 v[56:59], v5 offset:1024
	ds_read_b128 v[60:63], v5 offset:2048
	ds_read_b128 v[64:67], v5 offset:3072
	v_pk_mul_f32 v[8:9], v[8:9], v[48:49]
	v_pk_mul_f32 v[10:11], v[10:11], v[50:51]
	v_pk_mul_f32 v[12:13], v[12:13], v[48:49]
	v_pk_mul_f32 v[14:15], v[14:15], v[50:51]
	s_and_b32 s69, s54, 1
	s_mulk_i32 s69, 0x2200
	v_add_u32_e32 v6, s69, v3
	v_add_u32_e32 v7, s69, v4
	s_waitcnt lgkmcnt(0)
	s_nop 0
	v_mfma_f32_16x16x32_bf16 v[8:11], v[40:43], v[52:55], v[8:11]
	v_mfma_f32_16x16x32_bf16 v[12:15], v[40:43], v[60:63], v[12:15]
	v_mfma_f32_16x16x32_bf16 v[8:11], v[44:47], v[56:59], v[8:11]
	v_mfma_f32_16x16x32_bf16 v[12:15], v[44:47], v[64:67], v[12:15]
	global_load_dwordx4 v[28:31], v0, s[58:59]
	global_load_dwordx4 v[32:35], v0, s[58:59] offset:1024
	global_load_dwordx4 v[36:39], v1, s[60:61]
	s_add_u32 s58, s58, 0x4000
	s_addc_u32 s59, s59, 0
	s_add_u32 s60, s60, 0x200
	s_addc_u32 s61, s61, 0
	s_nop 7
	v_cvt_pk_bf16_f32 v104, v8, v9
	v_cvt_pk_bf16_f32 v105, v10, v11
	v_cvt_pk_bf16_f32 v106, v12, v13
	v_cvt_pk_bf16_f32 v107, v14, v15
	ds_write_b64 v6, v[104:105]
	ds_write_b64 v6, v[106:107] offset:4352
	s_waitcnt vmcnt(11)
	s_waitcnt lgkmcnt(0)
	s_barrier
	v_add_u32_e32 v5, s68, v108
	ds_read_b128 v[68:71], v7
	ds_read_b128 v[72:75], v7 offset:64
	ds_read_b128 v[76:79], v7 offset:128
	ds_read_b128 v[80:83], v7 offset:192
	ds_read_b128 v[84:87], v5
	ds_read_b128 v[88:91], v5 offset:1024
	ds_read_b128 v[92:95], v5 offset:2048
	ds_read_b128 v[96:99], v5 offset:3072
	s_add_i32 s0, s68, 0xffffb000
	s_cmp_lg_u32 s68, 0x5000
	s_cselect_b32 s0, s0, 0x14000
	s_mov_b64 exec, s[36:37]
	s_add_i32 m0, s0, s55
	s_nop 0
	global_load_lds_dwordx4 v109, s[62:63] nt
	s_mov_b64 exec, -1
	s_add_i32 m0, s0, s53
	s_nop 0
	global_load_lds_dwordx4 v0, s[64:65]
	global_load_lds_dwordx4 v0, s[64:65] offset:1024
	s_add_u32 s62, s62, 0x1000
	s_addc_u32 s63, s63, 0
	s_add_u32 s64, s64, 0x4000
	s_addc_u32 s65, s65, 0
	s_waitcnt lgkmcnt(0)
	v_mfma_f32_16x16x32_bf16 v[100:103], v[68:71], v[84:87], 0
	v_mfma_f32_16x16x32_bf16 v[100:103], v[72:75], v[88:91], v[100:103]
	v_mfma_f32_16x16x32_bf16 v[100:103], v[76:79], v[92:95], v[100:103]
	v_mfma_f32_16x16x32_bf16 v[100:103], v[80:83], v[96:99], v[100:103]
	s_add_i32 s68, s68, 0x5000
	s_cmp_lg_u32 s68, 0x19000
	s_cselect_b32 s68, s68, 0x5000
	s_nop 7
	v_pk_mul_f32 v[100:101], v[100:101], s[22:23] op_sel_hi:[1,0]
	v_pk_mul_f32 v[102:103], v[102:103], s[22:23] op_sel_hi:[1,0]
	s_cmpk_lt_u32 s54, 0x20
	v_cvt_pk_bf16_f32 v104, v100, v101
	v_cvt_pk_bf16_f32 v105, v102, v103
	s_cbranch_scc0 .Lgla_nost2
	global_store_dwordx2 v2, v[104:105], s[66:67]
